# GLA scan: intra-chunk matrix MFMA chain split over two accumulators (even/odd k-steps) and summed with packed adds
# speedup vs baseline: 1.0021x; 1.0021x over previous
; __device__ __forceinline__ unsigned pk2(float lo, float hi) { f32x2_t v = {lo, hi}; bf16x2_t b = __builtin_convertvector(v, bf16x2_t); return __builtin_bit_cast(unsigned, b); }
; #define OPAQUE_TID(name) int name = MK_TID; asm volatile("" : "+v"(name))
; __device__ __forceinline__ void scan_unit(const int unit, const Args& a, unsigned char* lds, const int mk_wid) {
;     ...
;             if (wid < 4) { OPAQUE_TID(t_); const int r32 = t_ & 31, hi = (t_ >> 5) & 1;
;                 const int jt = wid >> 1, it = wid & 1; f32x16 ct = f32x16{};
;                 const u16* kp = ke + (jt * 32 + r32) * QP + hi * 8; const u16* qp = qe + (it * 32 + r32) * QP + hi * 8;
; #pragma unroll
;                 for (int kb = 0; kb < 8; ++kb) ct = __builtin_amdgcn_mfma_f32_32x32x16_bf16(*(const bf16x8*)(kp + kb * 16), *(const bf16x8*)(qp + kb * 16), ct, 0, 0, 0);
;                 const int i = it * 32 + r32;
; #pragma unroll
;                 for (int rg = 0; rg < 4; ++rg) { const int j0 = jt * 32 + 8 * rg + 4 * hi;
;                     const float x0 = (j0 + 0 <= i) ? ct[4 * rg + 0] : 0.f, x1 = (j0 + 1 <= i) ? ct[4 * rg + 1] : 0.f, x2 = (j0 + 2 <= i) ? ct[4 * rg + 2] : 0.f, x3 = (j0 + 3 <= i) ? ct[4 * rg + 3] : 0.f;
;                     v2u w; w.x = pk2(x0, x1); w.y = pk2(x2, x3); *(v2u*)(am + i * AP + j0) = w; } }
.Lscan_pf_nolr:
.LBB0_435:
	s_cmp_gt_u32 s5, 3
	s_cselect_b32 s4, 39, 3
	s_add_i32 s4, s4, s50
	s_sub_i32 s4, s4, 38
	s_and_b64 s[26:27], s[2:3], exec
	s_cselect_b32 s42, s5, s4
	s_cmp_gt_i32 s42, 3
	s_cselect_b64 s[26:27], -1, 0
	s_cmp_lt_i32 s42, 4
	s_cselect_b64 s[34:35], -1, 0
	s_and_b64 vcc, exec, s[34:35]
	s_waitcnt lgkmcnt(0)
	s_barrier
	s_cbranch_vccnz .LBB0_439
	s_andn2_b64 vcc, exec, s[24:25]
	s_cbranch_vccnz .LBB0_438
	v_mbcnt_lo_u32_b32 v64, -1, 0
	v_mbcnt_hi_u32_b32 v64, -1, v64
	s_nop 0
	v_add_u32_e32 v64, s72, v64
	s_nop 0
	v_and_b32_e32 v68, 31, v64
	v_bfe_u32 v154, v64, 5, 1
	v_or_b32_e32 v64, s46, v68
	v_mul_lo_u32 v64, v64, s51
	v_lshlrev_b32_e32 v69, 4, v154
	v_add3_u32 v157, 0, v64, v69
	v_or_b32_e32 v158, s47, v68
	v_mul_u32_u24_e32 v68, 0x110, v158
	v_add3_u32 v159, 0, v68, v69
	ds_read_b128 v[170:173], v157 offset:17408
	ds_read_b128 v[174:177], v159
	ds_read_b128 v[178:181], v157 offset:17440
	ds_read_b128 v[182:185], v159 offset:32
	ds_read_b128 v[186:189], v157 offset:17472
	ds_read_b128 v[190:193], v159 offset:64
	ds_read_b128 v[194:197], v157 offset:17504
	ds_read_b128 v[198:201], v159 offset:96
	ds_read_b128 v[202:205], v157 offset:17536
	ds_read_b128 v[206:209], v159 offset:128
	ds_read_b128 v[210:213], v157 offset:17568
	ds_read_b128 v[214:217], v159 offset:160
	ds_read_b128 v[218:221], v157 offset:17600
	ds_read_b128 v[222:225], v159 offset:192
	ds_read_b128 v[226:229], v157 offset:17632
	v_lshl_or_b32 v154, v154, 2, s46
	v_cmp_le_u32_e32 vcc, v154, v158
	v_or_b32_e32 v161, 2, v154
	v_or_b32_e32 v162, 3, v154
	v_or_b32_e32 v164, 8, v154
	v_mul_u32_u24_e32 v160, 0x90, v158
	v_lshlrev_b32_e32 v163, 1, v154
	s_waitcnt lgkmcnt(13)
	v_mfma_f32_32x32x16_bf16 v[64:79], v[170:173], v[174:177], 0
	ds_read_b128 v[230:233], v159 offset:224
	v_or_b32_e32 v80, 10, v154
	v_or_b32_e32 v81, 11, v154
	v_or_b32_e32 v82, 16, v154
	v_or_b32_e32 v83, 18, v154
	v_or_b32_e32 v84, 19, v154
	v_or_b32_e32 v85, 24, v154
	v_add3_u32 v86, s57, v160, v163
	s_waitcnt lgkmcnt(12)
	v_mfma_f32_32x32x16_bf16 v[112:127], v[178:181], v[182:185], 0
	s_waitcnt lgkmcnt(10)
	v_mfma_f32_32x32x16_bf16 v[64:79], v[186:189], v[190:193], v[64:79]
	s_waitcnt lgkmcnt(8)
	v_mfma_f32_32x32x16_bf16 v[112:127], v[194:197], v[198:201], v[112:127]
	s_waitcnt lgkmcnt(6)
	v_mfma_f32_32x32x16_bf16 v[64:79], v[202:205], v[206:209], v[64:79]
	s_waitcnt lgkmcnt(4)
	v_mfma_f32_32x32x16_bf16 v[112:127], v[210:213], v[214:217], v[112:127]
	s_waitcnt lgkmcnt(2)
	v_mfma_f32_32x32x16_bf16 v[64:79], v[218:221], v[222:225], v[64:79]
	s_waitcnt lgkmcnt(0)
	v_mfma_f32_32x32x16_bf16 v[112:127], v[226:229], v[230:233], v[112:127]
	s_nop 11
	v_pk_add_f32 v[64:65], v[64:65], v[112:113]
	v_pk_add_f32 v[66:67], v[66:67], v[114:115]
	v_pk_add_f32 v[68:69], v[68:69], v[116:117]
	v_pk_add_f32 v[70:71], v[70:71], v[118:119]
	v_pk_add_f32 v[72:73], v[72:73], v[120:121]
	v_pk_add_f32 v[74:75], v[74:75], v[122:123]
	v_pk_add_f32 v[76:77], v[76:77], v[124:125]
	v_pk_add_f32 v[78:79], v[78:79], v[126:127]
	v_cndmask_b32_e32 v64, 0, v64, vcc
	v_cmp_lt_u32_e32 vcc, v154, v158
	s_nop 1
	v_cndmask_b32_e32 v65, 0, v65, vcc
	v_cmp_le_u32_e32 vcc, v161, v158
	v_cvt_pk_bf16_f32 v64, v64, v65
	s_nop 0
	v_cndmask_b32_e32 v66, 0, v66, vcc
	v_cmp_le_u32_e32 vcc, v162, v158
	s_nop 1
	v_cndmask_b32_e32 v67, 0, v67, vcc
	v_cmp_le_u32_e32 vcc, v164, v158
	v_cvt_pk_bf16_f32 v65, v66, v67
	s_nop 0
	v_cndmask_b32_e32 v68, 0, v68, vcc
	v_cmp_lt_u32_e32 vcc, v164, v158
	s_nop 1
	v_cndmask_b32_e32 v69, 0, v69, vcc
	v_cmp_le_u32_e32 vcc, v80, v158
	v_cvt_pk_bf16_f32 v66, v68, v69
	s_nop 0
	v_cndmask_b32_e32 v70, 0, v70, vcc
	v_cmp_le_u32_e32 vcc, v81, v158
	s_nop 1
	v_cndmask_b32_e32 v71, 0, v71, vcc
	v_cmp_le_u32_e32 vcc, v82, v158
	v_cvt_pk_bf16_f32 v67, v70, v71
	ds_write2_b64 v86, v[64:65], v[66:67] offset1:2
	v_cndmask_b32_e32 v72, 0, v72, vcc
	v_cmp_lt_u32_e32 vcc, v82, v158
	v_or_b32_e32 v65, 26, v154
	v_or_b32_e32 v66, 27, v154
	v_cndmask_b32_e32 v73, 0, v73, vcc
	v_cmp_le_u32_e32 vcc, v83, v158
	v_cvt_pk_bf16_f32 v68, v72, v73
	s_nop 0
	v_cndmask_b32_e32 v74, 0, v74, vcc
	v_cmp_le_u32_e32 vcc, v84, v158
	s_nop 1
	v_cndmask_b32_e32 v75, 0, v75, vcc
	v_cmp_le_u32_e32 vcc, v85, v158
	v_cvt_pk_bf16_f32 v69, v74, v75
	s_nop 0
	v_cndmask_b32_e32 v76, 0, v76, vcc
	v_cmp_lt_u32_e32 vcc, v85, v158
	s_nop 1
	v_cndmask_b32_e32 v64, 0, v77, vcc
	v_cmp_le_u32_e32 vcc, v65, v158
	v_cvt_pk_bf16_f32 v64, v76, v64
	s_nop 0
	v_cndmask_b32_e32 v65, 0, v78, vcc
	v_cmp_le_u32_e32 vcc, v66, v158
	s_nop 1
	v_cndmask_b32_e32 v66, 0, v79, vcc
	v_cvt_pk_bf16_f32 v65, v65, v66
	ds_write2_b64 v86, v[68:69], v[64:65] offset0:4 offset1:6
